# speedup vs baseline: 1.0317x; 1.0039x over previous
; __device__ __forceinline__ float bf2f(u16 h) { return __uint_as_float(((unsigned)h) << 16); }
; __device__ __forceinline__ void scan_block(const int WV, const Params& P, int layer, int bh, int hv) {
;     ...
;   auto issue = [&](int chunk) {
;     size_t t = tbase + (size_t)chunk * SCH + htok;
;     const u16* zr = z + t * DIN + hch;
;     size_t ri = t * 1024 + hch;
;     Lr = *(const unsigned*)zr; Lk = *(const unsigned*)(zr + 1024); Lv = z[t * DIN + 2048 + hrow];
;     Lw = *(const unsigned*)(rwW + ri); Lkk = *(const unsigned*)(rwKK + ri); Lb = *(const unsigned*)(rwB + ri);
;     Lgn = rwG[t * 1024 + hrow];
;   };
;     ...
;   auto prefetch_partner = [&](int chunk) {
;     const int slot = (chunk & 1) * (SCH * 2);
;     pg1 = __hip_atomic_load(xpart + slot, __ATOMIC_RELAXED, __HIP_MEMORY_SCOPE_AGENT);
;     pg2 = __hip_atomic_load(xpart + slot + 1, __ATOMIC_RELAXED, __HIP_MEMORY_SCOPE_AGENT);
;   };
;   auto post_b = [&](int chunk, unsigned epoch) {
;     size_t t = tbase + (size_t)chunk * SCH + htok;
;     const int slot = (chunk & 1) * (SCH * 2);
;     for (unsigned spins = 0; spins < (1u << 22); ++spins) {
;       bool ok = ((unsigned)(pg1 >> 32) == epoch) && ((unsigned)(pg2 >> 32) == epoch);
;       if (__all(ok)) break;
;       __builtin_amdgcn_s_sleep(1);
;       pg1 = __hip_atomic_load(xpart + slot, __ATOMIC_RELAXED, __HIP_MEMORY_SCOPE_AGENT);
;       pg2 = __hip_atomic_load(xpart + slot + 1, __ATOMIC_RELAXED, __HIP_MEMORY_SCOPE_AGENT);
;     }
;     float p1 = __uint_as_float((unsigned)pg1), p2 = __uint_as_float((unsigned)pg2);
;     float mean = (Ps1 + p1) * (1.f / 64.f);
;     float var = (Ps2 + p2) * (1.f / 64.f) - mean * mean;
;     float rstd = rsqrtf(fmaxf(var, 0.f) + GN_EPS);
;     float o = ((Py - mean) * rstd * gw1 + gb1 + Pbon) * bf2f(Pg);
;     z[t * DIN + hrow] = f2bf(o);
;   };
;     ...
;     {
;       const float* base = ring + (size_t)buf * SCH * 384;
;       float* yb = ypart + (size_t)buf * (SCH * 512) + yoff;
;       f32x4 Ank, Aw, Ab, Ak, Ar, Bnk, Bw, Bb, Bk, Br; float Av, Bv;
;       SCAN_LOAD(A, base);
; #pragma unroll 2
;       for (int tok = 0; tok < SCH; tok += 2) {
;         SCAN_LOAD(B, base + (tok + 1) * 384);
;         SCAN_STEP(A, yb + tok * 512);
;         SCAN_LOAD(A, base + ((tok + 2) & (SCH - 1)) * 384);
;         SCAN_STEP(B, yb + (tok + 1) * 512);
;       }
;     }
.LBB0_297:
	s_cmp_lg_i32 s20, -2
	s_cbranch_scc1 .Liss_skip
	s_cmpk_gt_u32 s22, 0x3fd
	s_cbranch_scc1 .Liss_skip
	s_add_i32 s80, s22, 2
	s_lshl_b32 s80, s80, 4
	v_lshl_add_u64 v[242:243], v[34:35], 0, s[80:81]
	v_mov_b64_e32 v[244:245], s[46:47]
	v_mad_u64_u32 v[244:245], s[6:7], v242, s90, v[244:245]
	v_mad_i32_i24 v245, v243, s90, v245
	v_lshl_add_u64 v[246:247], v[244:245], 0, v[0:1]
	global_load_dword v64, v[246:247], off
	global_load_dword v65, v[246:247], off offset:2048
	v_lshlrev_b32_e32 v246, 1, v22
	v_mov_b32_e32 v247, v1
	v_lshl_add_u64 v[244:245], v[244:245], 0, v[246:247]
	v_add_co_u32_e32 v244, vcc, s36, v244
	v_lshlrev_b64 v[242:243], 11, v[242:243]
	s_nop 0
	v_addc_co_u32_e32 v245, vcc, 0, v245, vcc
	global_load_ushort v66, v[244:245], off
	v_or_b32_e32 v244, v242, v0
	v_mov_b32_e32 v245, v243
	v_lshl_add_u64 v[246:247], s[62:63], 0, v[244:245]
	global_load_dword v67, v[246:247], off
	v_lshl_add_u64 v[246:247], s[64:65], 0, v[244:245]
	v_lshl_add_u64 v[244:245], s[66:67], 0, v[244:245]
	v_lshl_add_u64 v[242:243], v[38:39], 0, v[242:243]
	global_load_dword v68, v[246:247], off
	global_load_dword v69, v[244:245], off
	global_load_ushort v70, v[242:243], off
.Liss_skip:
	s_cmp_lg_u32 s20, 10
	s_cbranch_scc1 .Lpp_skip
	global_load_dwordx2 v[42:43], v[254:255], off sc1
	global_load_dwordx2 v[44:45], v[254:255], off offset:8 sc1
.Lpp_skip:
	ds_read_b128 v[76:79], v74
	ds_read_b128 v[80:83], v74 offset:256
	ds_read_b128 v[84:87], v74 offset:512
	ds_read_b128 v[88:91], v74 offset:768
	ds_read_b128 v[92:95], v74 offset:1024
	ds_read_b32 v96, v73
	s_waitcnt lgkmcnt(6)
	v_mul_f32 v97, v60, v2
	v_fmac_f32 v97, v61, v3
	v_fmac_f32 v97, v62, v4
	v_fmac_f32 v97, v63, v5
	v_mul_f32 v99, v60, v6
	v_mul_f32 v100, v61, v7
	v_add_f32_dpp v97, v97, v97 row_ror:8 row_mask:0xf bank_mask:0xf
	v_mul_f32 v101, v62, v8
	v_mul_f32 v102, v63, v9
	v_add_f32_dpp v97, v97, v97 row_ror:4 row_mask:0xf bank_mask:0xf
	v_fmac_f32 v99, v75, v14
	v_fmac_f32 v100, v75, v15
	v_add_f32_dpp v97, v97, v97 row_ror:2 row_mask:0xf bank_mask:0xf
	v_fmac_f32 v101, v75, v16
	v_fmac_f32 v102, v75, v17
	v_add_f32_dpp v97, v97, v97 row_ror:1 row_mask:0xf bank_mask:0xf
	v_fma_f32 v60, v97, v10, v99
	v_fma_f32 v61, v97, v11, v100
	v_fma_f32 v62, v97, v12, v101
	v_fma_f32 v63, v97, v13, v102
	v_mul_f32 v98, v60, v18
	v_fmac_f32 v98, v61, v19
	v_fmac_f32 v98, v62, v20
	v_fmac_f32 v98, v63, v21
	ds_write_b32 v72, v98
	ds_read_b128 v[2:5], v74 offset:1536
	ds_read_b128 v[6:9], v74 offset:1792
	ds_read_b128 v[10:13], v74 offset:2048
	ds_read_b128 v[14:17], v74 offset:2304
	ds_read_b128 v[18:21], v74 offset:2560
	ds_read_b32 v75, v73 offset:1536
	s_add_i32 s21, s20, 6
	s_and_b32 s21, s21, 12
	s_mulk_i32 s21, 0x600
	s_waitcnt lgkmcnt(7)
	v_mul_f32 v97, v60, v76
	v_fmac_f32 v97, v61, v77
	v_fmac_f32 v97, v62, v78
	v_fmac_f32 v97, v63, v79
	v_mul_f32 v99, v60, v80
	v_mul_f32 v100, v61, v81
	v_add_f32_dpp v97, v97, v97 row_ror:8 row_mask:0xf bank_mask:0xf
	v_mul_f32 v101, v62, v82
	v_mul_f32 v102, v63, v83
	v_add_f32_dpp v97, v97, v97 row_ror:4 row_mask:0xf bank_mask:0xf
	v_fmac_f32 v99, v96, v88
	v_fmac_f32 v100, v96, v89
	v_add_f32_dpp v97, v97, v97 row_ror:2 row_mask:0xf bank_mask:0xf
	v_fmac_f32 v101, v96, v90
	v_fmac_f32 v102, v96, v91
	v_add_f32_dpp v97, v97, v97 row_ror:1 row_mask:0xf bank_mask:0xf
	v_fma_f32 v60, v97, v84, v99
	v_fma_f32 v61, v97, v85, v100
	v_fma_f32 v62, v97, v86, v101
	v_fma_f32 v63, v97, v87, v102
	v_mul_f32 v98, v60, v92
	v_fmac_f32 v98, v61, v93
	v_fmac_f32 v98, v62, v94
	v_fmac_f32 v98, v63, v95
	ds_write_b32 v72, v98 offset:2048
	s_add_i32 s21, s13, s21
	ds_read_b128 v[76:79], v74 offset:3072
	ds_read_b128 v[80:83], v74 offset:3328
	ds_read_b128 v[84:87], v74 offset:3584
	ds_read_b128 v[88:91], v74 offset:3840
	ds_read_b128 v[92:95], v74 offset:4096
	ds_read_b32 v96, v73 offset:3072
	s_waitcnt lgkmcnt(7)
	v_mul_f32 v97, v60, v2
	v_fmac_f32 v97, v61, v3
	v_fmac_f32 v97, v62, v4
	v_fmac_f32 v97, v63, v5
	v_mul_f32 v99, v60, v6
	v_mul_f32 v100, v61, v7
	v_add_f32_dpp v97, v97, v97 row_ror:8 row_mask:0xf bank_mask:0xf
	v_mul_f32 v101, v62, v8
	v_mul_f32 v102, v63, v9
	v_add_f32_dpp v97, v97, v97 row_ror:4 row_mask:0xf bank_mask:0xf
	v_fmac_f32 v99, v75, v14
	v_fmac_f32 v100, v75, v15
	v_add_f32_dpp v97, v97, v97 row_ror:2 row_mask:0xf bank_mask:0xf
	v_fmac_f32 v101, v75, v16
	v_fmac_f32 v102, v75, v17
	v_add_f32_dpp v97, v97, v97 row_ror:1 row_mask:0xf bank_mask:0xf
	v_fma_f32 v60, v97, v10, v99
	v_fma_f32 v61, v97, v11, v100
	v_fma_f32 v62, v97, v12, v101
	v_fma_f32 v63, v97, v13, v102
	v_mul_f32 v98, v60, v18
	v_fmac_f32 v98, v61, v19
	v_fmac_f32 v98, v62, v20
	v_fmac_f32 v98, v63, v21
	ds_write_b32 v72, v98 offset:4096
	v_lshl_add_u32 v18, v53, 2, s21
	ds_read_b128 v[2:5], v18
	ds_read_b128 v[6:9], v18 offset:256
	ds_read_b128 v[10:13], v18 offset:512
	ds_read_b128 v[14:17], v18 offset:768
	v_lshl_add_u32 v75, v56, 2, s21
	ds_read_b128 v[18:21], v18 offset:1024
	ds_read_b32 v75, v75 offset:1280
	s_add_i32 s20, s20, 4
	s_waitcnt lgkmcnt(7)
	v_mul_f32 v97, v60, v76
	v_fmac_f32 v97, v61, v77
	v_fmac_f32 v97, v62, v78
	v_fmac_f32 v97, v63, v79
	v_mul_f32 v99, v60, v80
	v_mul_f32 v100, v61, v81
	v_add_f32_dpp v97, v97, v97 row_ror:8 row_mask:0xf bank_mask:0xf
	v_mul_f32 v101, v62, v82
	v_mul_f32 v102, v63, v83
	v_add_f32_dpp v97, v97, v97 row_ror:4 row_mask:0xf bank_mask:0xf
	v_fmac_f32 v99, v96, v88
	v_fmac_f32 v100, v96, v89
	v_add_f32_dpp v97, v97, v97 row_ror:2 row_mask:0xf bank_mask:0xf
	v_fmac_f32 v101, v96, v90
	v_fmac_f32 v102, v96, v91
	v_add_f32_dpp v97, v97, v97 row_ror:1 row_mask:0xf bank_mask:0xf
	v_fma_f32 v60, v97, v84, v99
	v_fma_f32 v61, v97, v85, v100
	v_fma_f32 v62, v97, v86, v101
	v_fma_f32 v63, v97, v87, v102
	v_mul_f32 v98, v60, v92
	v_fmac_f32 v98, v61, v93
	v_fmac_f32 v98, v62, v94
	v_fmac_f32 v98, v63, v95
	ds_write_b32 v72, v98 offset:6144
	v_add_u32_e32 v72, 0x2000, v72
	v_add_u32_e32 v73, 0x1800, v73
	s_cmp_gt_u32 s20, 13
	v_add_u32_e32 v74, 0x1800, v74
	s_cbranch_scc0 .LBB0_297
	s_cmp_eq_u32 s22, 0
	s_cbranch_scc1 .Lpb_skip
	s_add_i32 s80, s22, s31
	v_mov_b32_e32 v204, s80

; #define LDS_BARRIER() do { asm volatile("s_waitcnt lgkmcnt(0)" ::: "memory"); __builtin_amdgcn_s_barrier(); asm volatile("" ::: "memory"); } while (0)
; __device__ __forceinline__ void scan_block(const int WV, const Params& P, int layer, int bh, int hv) {
;     ...
;     LDS_BARRIER();
;     if (chunk >= 1) post_b(chunk - 1, (unsigned)(layer * 2048 + chunk));
.Lpb_skip:
	s_waitcnt lgkmcnt(0)
	s_barrier
	s_branch .LBB0_332

; __device__ __forceinline__ void scan_block(const int WV, const Params& P, int layer, int bh, int hv) {
;     ...
;     if (chunk + 1 < NCH) { commit(buf ^ 1); Lg1 = Lgn; }
;     if (chunk + 2 < NCH) {
;       if (!prep_all_done && ((chunk + 2) >> 1) >= next_check) {
;         if (__hip_atomic_load((const gu32*)pdone_s, __ATOMIC_RELAXED, __HIP_MEMORY_SCOPE_AGENT) >= gridDim.x - 64) {
;           __builtin_amdgcn_fence(__ATOMIC_ACQUIRE, "agent");
;           prep_all_done = true;
;         } else {
;           const int t0w = (chunk + 2) >> 1;
;           wait_flags16(tflag + t0w, min(64, 512 - t0w), lane);
;           next_check = t0w + 64;
;         }
;       }
;       issue(chunk + 2);
;     }
;     if (chunk >= 1) prefetch_partner(chunk - 1);
.LBB0_337:
	s_cmp_lg_u32 s22, 0
	s_cselect_b64 s[6:7], -1, 0
	s_cmp_eq_u32 s22, 0
	s_cbranch_scc0 .LBB0_295
	s_branch .LBB0_296
